# nt cache policy on the 13 read-once dwordx4 loads of fnet-combine, attn-combine and fold loops
# speedup vs baseline: 1.0054x; 1.0054x over previous
; __device__ __forceinline__ void phase_fold(const bf16_t* __restrict__ zt, bf16_t* __restrict__ zf, float* __restrict__ ph, const int nseq, const int S) {
;     ...
;     for (int j = lane * 8; j < K2; j += 512) {
;       unsigned z = 0; asm volatile("" : "+v"(z));
;       uint4 oe = make_uint4(z, z, z, z), oo = oe;
;       if (j <= Q4) {
;         const uint4 w1 = *(const uint4*)(a + j), w2 = *(const uint4*)(a + S - j - 8), w3 = *(const uint4*)(a + H - j - 8), w4 = *(const uint4*)(a + H + j);
;         const float s2 = (j > 0) ? __uint_as_float(((unsigned)a[S - j]) << 16) : 0.f;
;         const float s3 = __uint_as_float(((unsigned)a[H - j]) << 16);
.LBB0_326:
	v_mov_b32_e32 v2, v81
	v_cmp_ge_u32_e32 vcc, s13, v31
	v_mov_b32_e32 v3, v2
	v_mov_b64_e32 v[0:1], v[2:3]
	v_mov_b64_e32 v[6:7], v[2:3]
	v_mov_b64_e32 v[4:5], v[2:3]
	s_and_saveexec_b64 s[8:9], vcc
	s_xor_b64 s[96:97], exec, s[8:9]
	s_cbranch_execz .LBB0_325
	v_lshl_add_u64 v[0:1], v[38:39], 0, v[32:33]
	v_add_co_u32_e32 v0, vcc, 0x18180000, v0
	v_lshl_add_u64 v[4:5], v[44:45], 0, v[32:33]
	s_nop 0
	v_addc_co_u32_e32 v1, vcc, 0, v1, vcc
	v_add_co_u32_e32 v4, vcc, 0x1817f000, v4
	v_lshl_add_u64 v[8:9], v[42:43], 0, v[32:33]
	s_nop 0
	v_addc_co_u32_e32 v5, vcc, 0, v5, vcc
	v_add_co_u32_e32 v8, vcc, 0x1817f000, v8
	v_lshl_add_u64 v[12:13], v[40:41], 0, v[32:33]
	s_nop 0
	v_addc_co_u32_e32 v9, vcc, 0, v9, vcc
	v_add_co_u32_e32 v12, vcc, 0x18180000, v12
	global_load_dwordx4 v[0:3], v[0:1], off nt
	s_nop 0
	v_addc_co_u32_e32 v13, vcc, 0, v13, vcc
	global_load_dwordx4 v[4:7], v[4:5], off offset:4080 nt
	v_cmp_eq_u32_e32 vcc, 0, v31
	global_load_dwordx4 v[8:11], v[8:9], off offset:4080 nt
	v_cmp_ne_u32_e64 s[8:9], 0, v31
	global_load_dwordx4 v[12:15], v[12:13], off nt
	v_add_u32_e32 v80, s40, v46
	v_lshl_add_u64 v[102:103], v[80:81], 1, v[34:35]
	global_load_ushort v100, v[102:103], off
	v_mov_b32_e32 v52, 0
	s_and_saveexec_b64 s[18:19], s[8:9]
	s_cbranch_execz .LBB0_329
	v_add_u32_e32 v80, s17, v46
	v_lshl_add_u64 v[48:49], v[80:81], 1, v[34:35]
	global_load_ushort v48, v[48:49], off
	s_waitcnt vmcnt(0) lgkmcnt(0)
	v_lshlrev_b32_e32 v52, 16, v48

; __device__ __forceinline__ void phase_fnet_combine(bf16_t* __restrict__ fg, const float* __restrict__ P, const float* __restrict__ Q, const float* __restrict__ P128, const float* __restrict__ PH, const int S) {
;     ...
;     const size_t t = i >> 9; const int col = (int)(i & 511) * 8, g = col >> 8, l0 = col & 255;
;     const int seq = (int)(t / S), k = (int)(t % S);
;     const bool klo = (k <= S / 2); const int kk = klo ? k : S - k;
;     const bool mid = (kk == S / 2), hi = (l0 >= 128);
;     const float* Pr = mid ? PH + seq * 2304 : P + ((size_t)seq * 4096 + kk) * 2048;
;     const float* Qr = Q + ((size_t)seq * 4096 + (mid ? 0 : kk)) * 2048;
;     const int vb = g * 128 + (hi ? 248 - l0 : l0);
;     const f32x4 p0 = *(const f32x4*)(Pr + vb), p1 = *(const f32x4*)(Pr + vb + 4);
;     const f32x4 q0 = *(const f32x4*)(Qr + vb), q1 = *(const f32x4*)(Qr + vb + 4);
;     const float pw[8] = {p0[0], p0[1], p0[2], p0[3], p1[0], p1[1], p1[2], p1[3]}, qw[8] = {q0[0], q0[1], q0[2], q0[3], q1[0], q1[1], q1[2], q1[3]};
;     float ps = 0.f, qs = 0.f;
;     if (hi) {
;       if (l0 == 128) ps = mid ? PH[seq * 2304 + 2048 + g] : P128[((size_t)seq * 4096 + kk) * 16 + g];
;       else { ps = Pr[g * 128 + 256 - l0]; qs = Qr[g * 128 + 256 - l0]; }
;     }
;     const float sq = (mid ? 0.f : 1.f) * (klo ? 1.f : -1.f) * (hi ? -1.f : 1.f);
;     bf16_t* gp = fg + t * 4096 + col;
;     const uint4 gt = *(const uint4*)gp;
;     const unsigned gu[4] = {gt.x, gt.y, gt.z, gt.w};
.LBB0_477:
	v_alignbit_b32 v0, v37, v36, 9
	v_lshrrev_b32_e32 v80, s0, v0
	v_and_b32_e32 v0, s1, v0
	v_sub_u32_e32 v1, s17, v0
	v_cmp_lt_u32_e64 s[2:3], s40, v0
	s_nop 1
	v_cndmask_b32_e64 v0, v0, v1, s[2:3]
	v_cmp_eq_u32_e64 s[4:5], s40, v0
	v_cmp_ne_u32_e64 s[6:7], s40, v0
	s_and_saveexec_b64 s[8:9], s[6:7]
	s_xor_b64 s[8:9], exec, s[8:9]
	v_ashrrev_i32_e32 v1, 31, v0
	v_lshlrev_b64 v[2:3], 25, v[80:81]
	v_lshl_add_u64 v[2:3], s[94:95], 0, v[2:3]
	v_lshlrev_b64 v[4:5], 13, v[0:1]
	v_lshl_add_u64 v[2:3], v[2:3], 0, v[4:5]
	v_mov_b64_e32 v[4:5], v[0:1]
	s_andn2_saveexec_b64 s[8:9], s[8:9]
	v_mov_b64_e32 v[2:3], s[44:45]
	s_movk_i32 s13, 0x2400
	v_mad_u64_u32 v[2:3], s[18:19], v80, s13, v[2:3]
	v_mov_b64_e32 v[4:5], 0
	s_or_b64 exec, exec, s[8:9]
	v_lshlrev_b64 v[38:39], 12, v[80:81]
	v_lshl_add_u64 v[4:5], v[4:5], 0, v[38:39]
	v_lshlrev_b64 v[4:5], 13, v[4:5]
	s_movk_i32 s8, 0xf8
	v_and_b32_e32 v45, 0xf8, v44
	v_lshl_add_u64 v[40:41], s[96:97], 0, v[4:5]
	v_bitop3_b32 v4, v44, s8, v44 bitop3:0xc
	s_movk_i32 s8, 0x7f
	v_bfe_u32 v48, v44, 8, 4
	v_cmp_lt_u32_e32 vcc, s8, v45
	v_lshlrev_b32_e32 v1, 7, v48
	v_mov_b32_e32 v13, v81
	v_cndmask_b32_e32 v4, v45, v4, vcc
	v_add_lshl_u32 v12, v1, v4, 2
	v_lshl_add_u64 v[8:9], v[2:3], 0, v[12:13]
	v_lshl_add_u64 v[16:17], v[40:41], 0, v[12:13]
	s_movk_i32 s100, 0x80
	v_cmp_eq_u32_e64 s[100:101], s100, v45
	v_ashrrev_i32_e32 v109, 31, v0
	v_mov_b32_e32 v108, v0
	v_lshl_add_u64 v[108:109], v[38:39], 0, v[108:109]
	v_lshlrev_b64 v[108:109], 6, v[108:109]
	v_lshl_add_u64 v[108:109], s[42:43], 0, v[108:109]
	v_lshlrev_b32_e32 v110, 2, v48
	v_mov_b32_e32 v111, v81
	v_lshl_add_u64 v[108:109], v[108:109], 0, v[110:111]
	v_mul_u32_u24_e32 v110, 0x900, v80
	v_or_b32_e32 v110, v110, v48
	v_add_u32_e32 v110, 0x800, v110
	v_lshl_add_u64 v[112:113], v[110:111], 2, s[44:45]
	v_cndmask_b32_e64 v108, v108, v112, s[4:5]
	v_cndmask_b32_e64 v109, v109, v113, s[4:5]
	v_lshl_add_u64 v[112:113], v[8:9], 0, 32
	v_cndmask_b32_e64 v108, v112, v108, s[100:101]
	v_cndmask_b32_e64 v109, v113, v109, s[100:101]
	global_load_dword v106, v[108:109], off
	global_load_dword v107, v[16:17], off offset:32
	v_lshl_add_u64 v[104:105], v[36:37], 4, s[38:39]
	global_load_dwordx4 v[100:103], v[104:105], off nt
	global_load_dwordx4 v[4:7], v[8:9], off nt
	s_nop 0
	global_load_dwordx4 v[8:11], v[8:9], off offset:16 nt
	s_nop 0
	global_load_dwordx4 v[12:15], v[16:17], off offset:16 nt
	s_nop 0
	global_load_dwordx4 v[16:19], v[16:17], off nt
	v_mov_b32_e32 v47, 0
	v_mov_b32_e32 v49, 1.0
	v_mov_b32_e32 v46, 0
	s_waitcnt vmcnt(0) lgkmcnt(0)
	v_mov_b64_e32 v[30:31], v[6:7]
	v_mov_b64_e32 v[22:23], v[10:11]
	v_mov_b64_e32 v[26:27], v[14:15]
	v_mov_b64_e32 v[34:35], v[18:19]
	v_mov_b64_e32 v[20:21], v[8:9]
	v_mov_b64_e32 v[28:29], v[4:5]
	v_mov_b64_e32 v[24:25], v[12:13]
	v_mov_b64_e32 v[32:33], v[16:17]
	s_and_saveexec_b64 s[46:47], vcc
	s_cbranch_execz .LBB0_476
	s_movk_i32 s8, 0x80
	v_cmp_ne_u32_e64 s[8:9], s8, v45
	s_and_saveexec_b64 s[18:19], s[8:9]
	s_xor_b64 s[8:9], exec, s[18:19]
	s_cbranch_execz .LBB0_484
	v_sub_u32_e32 v0, v1, v45
	v_add_u32_e32 v80, 0x100, v0
	v_lshlrev_b64 v[0:1], 2, v[80:81]
	v_lshl_add_u64 v[2:3], v[2:3], 0, v[0:1]
	v_lshl_add_u64 v[0:1], v[40:41], 0, v[0:1]
	v_mov_b32_e32 v46, v106
	v_mov_b32_e32 v47, v107

; __device__ __forceinline__ void phase_attn_combine(const bf16_t* __restrict__ qh, const bf16_t* __restrict__ gate, const float* __restrict__ lse, bf16_t* __restrict__ y, const int S) {
;     ...
;     const size_t t = i >> 8; const int col = (int)(i & 255) * 8, h16 = col >> 7, dd = col & 127;
;     const int seq = (int)(t / S), n = (int)(t % S);
;     const size_t p0 = t, p1 = (size_t)seq * S + (size_t)(n & 3) * (S >> 2) + (n >> 2), p2 = (size_t)seq * S + (size_t)(n & 15) * (S >> 4) + (n >> 4);
;     const float l0 = lse[(size_t)h16 * TS + p0], l1 = lse[(size_t)(16 + h16) * TS + p1], l2 = lse[(size_t)(32 + h16) * TS + p2];
;     const float mx = fmaxf(l0, fmaxf(l1, l2));
;     float w0 = __expf(l0 - mx), w1 = __expf(l1 - mx), w2 = __expf(l2 - mx);
;     const float wi = 1.f / (w0 + w1 + w2); w0 *= wi; w1 *= wi; w2 *= wi;
;     const uint4 a = *(const uint4*)(qh + ((size_t)h16 * TS + p0) * 128 + dd), b = *(const uint4*)(qh + ((size_t)(16 + h16) * TS + p1) * 128 + dd),
;                 c = *(const uint4*)(qh + ((size_t)(32 + h16) * TS + p2) * 128 + dd);
;     const uint4 gt = *(const uint4*)(gate + t * 2048 + col);
.LBB0_775:
	v_alignbit_b32 v5, v1, v0, 8
	v_cmp_le_u32_e32 vcc, s17, v5
	v_mov_b32_e32 v6, s17
	v_lshrrev_b64 v[2:3], 8, v[0:1]
	v_cndmask_b32_e32 v6, 0, v6, vcc
	v_sub_u32_e32 v5, v5, v6
	v_and_b32_e32 v80, 3, v5
	v_sub_co_u32_e32 v6, vcc, v2, v5
	v_lshlrev_b64 v[8:9], s0, v[80:81]
	v_lshrrev_b32_e32 v80, 2, v5
	v_and_b32_e32 v10, 15, v5
	v_lshrrev_b32_e32 v12, 4, v5
	v_lshlrev_b32_e32 v5, 10, v0
	v_and_b32_e32 v5, 0x3c000, v5
	v_or_b32_e32 v14, v2, v5
	v_mov_b32_e32 v15, v3
	v_lshl_add_u64 v[16:17], v[14:15], 2, s[36:37]
	v_subbrev_co_u32_e32 v7, vcc, 0, v3, vcc
	global_load_dword v20, v[16:17], off
	v_or_b32_e32 v16, 0x40000, v5
	v_mov_b32_e32 v17, v81
	v_lshl_add_u64 v[16:17], v[6:7], 0, v[16:17]
	v_lshl_add_u64 v[16:17], v[16:17], 0, v[80:81]
	v_or_b32_e32 v80, 0x80000, v5
	v_mov_b32_e32 v11, v81
	v_mov_b32_e32 v13, v81
	v_lshl_add_u64 v[6:7], v[6:7], 0, v[80:81]
	v_lshlrev_b64 v[10:11], s1, v[10:11]
	v_lshl_add_u64 v[6:7], v[6:7], 0, v[12:13]
	v_lshl_add_u64 v[16:17], v[16:17], 0, v[8:9]
	v_lshl_add_u64 v[18:19], v[6:7], 0, v[10:11]
	v_lshl_add_u64 v[8:9], v[16:17], 2, s[36:37]
	v_lshl_add_u64 v[6:7], v[18:19], 2, s[36:37]
	global_load_dword v8, v[8:9], off
	v_lshlrev_b64 v[2:3], 12, v[2:3]
	global_load_dword v5, v[6:7], off
	s_nop 1
	v_lshlrev_b32_e32 v112, 4, v0
	v_and_b32_e32 v114, 0xf0, v112
	v_lshlrev_b64 v[116:117], 8, v[14:15]
	v_lshl_add_u64 v[118:119], s[4:5], 0, v[116:117]
	v_mov_b32_e32 v116, v114
	v_mov_b32_e32 v117, v81
	v_lshl_add_u64 v[120:121], v[118:119], 0, v[116:117]
	global_load_dwordx4 v[96:99], v[120:121], off nt
	v_lshlrev_b64 v[116:117], 8, v[16:17]
	v_lshl_add_u64 v[118:119], s[4:5], 0, v[116:117]
	v_mov_b32_e32 v116, v114
	v_mov_b32_e32 v117, v81
	v_lshl_add_u64 v[120:121], v[118:119], 0, v[116:117]
	global_load_dwordx4 v[100:103], v[120:121], off nt
	v_lshlrev_b64 v[116:117], 8, v[18:19]
	v_lshl_add_u64 v[118:119], s[4:5], 0, v[116:117]
	v_mov_b32_e32 v116, v114
	v_mov_b32_e32 v117, v81
	v_lshl_add_u64 v[120:121], v[118:119], 0, v[116:117]
	global_load_dwordx4 v[104:107], v[120:121], off nt
	v_lshl_add_u64 v[114:115], s[8:9], 0, v[2:3]
	v_and_b32_e32 v116, 0xff0, v112
	v_mov_b32_e32 v118, v116
	v_mov_b32_e32 v119, v81
	v_lshl_add_u64 v[120:121], v[114:115], 0, v[118:119]
	global_load_dwordx4 v[108:111], v[120:121], off nt
	s_waitcnt lgkmcnt(0)
	s_waitcnt vmcnt(4)
	v_max3_f32 v6, v20, v8, v5
	v_sub_f32_e32 v7, v20, v6
	v_sub_f32_e32 v8, v8, v6
	v_mul_f32_e32 v7, 0x3fb8aa3b, v7
	v_mul_f32_e32 v8, 0x3fb8aa3b, v8
	v_sub_f32_e32 v5, v5, v6
	v_exp_f32_e32 v7, v7
	v_exp_f32_e32 v8, v8
	v_mul_f32_e32 v5, 0x3fb8aa3b, v5
	v_exp_f32_e32 v5, v5
	v_lshlrev_b32_e32 v20, 4, v0
	v_add_f32_e32 v6, v7, v8
	v_and_b32_e32 v80, 0xf0, v20
	v_add_f32_e32 v6, v5, v6
	v_div_scale_f32 v9, s[18:19], v6, v6, 1.0
	v_rcp_f32_e32 v10, v9
	v_lshl_add_u64 v[0:1], v[0:1], 0, s[14:15]
	v_fma_f32 v11, -v9, v10, 1.0
	v_fmac_f32_e32 v10, v11, v10
	v_div_scale_f32 v11, vcc, 1.0, v6, 1.0
	v_mul_f32_e32 v12, v11, v10
	v_fma_f32 v13, -v9, v12, v11
	v_fmac_f32_e32 v12, v13, v10
	v_fma_f32 v9, -v9, v12, v11
	v_div_fmas_f32 v9, v9, v10, v12
	v_div_fixup_f32 v6, v9, v6, 1.0
	v_mul_f32_e32 v22, v7, v6
	v_mul_f32_e32 v23, v8, v6
	v_mul_f32_e32 v5, v5, v6
	v_lshlrev_b64 v[6:7], 8, v[14:15]
	v_lshlrev_b64 v[10:11], 8, v[16:17]
	v_lshl_add_u64 v[6:7], s[4:5], 0, v[6:7]
	v_lshl_add_u64 v[10:11], s[4:5], 0, v[10:11]
	v_lshl_add_u64 v[6:7], v[6:7], 0, v[80:81]
	v_lshl_add_u64 v[10:11], v[10:11], 0, v[80:81]
	v_lshlrev_b64 v[14:15], 8, v[18:19]
	s_nop 0
	v_lshl_add_u64 v[14:15], s[4:5], 0, v[14:15]
	s_nop 0
	v_lshl_add_u64 v[14:15], v[14:15], 0, v[80:81]
	v_lshl_add_u64 v[18:19], s[8:9], 0, v[2:3]
	v_and_b32_e32 v80, 0xff0, v20
	s_nop 0
	v_lshl_add_u64 v[18:19], v[18:19], 0, v[80:81]
	s_nop 0
	v_lshl_add_u64 v[2:3], s[40:41], 0, v[2:3]
	v_lshl_add_u64 v[2:3], v[2:3], 0, v[80:81]
	s_waitcnt lgkmcnt(0)
	s_waitcnt vmcnt(3)
	v_lshlrev_b32_e32 v25, 16, v96
	v_and_b32_e32 v6, 0xffff0000, v96
	s_waitcnt vmcnt(2)
	v_lshlrev_b32_e32 v26, 16, v100
	v_mul_f32_e32 v26, v23, v26
	v_fmac_f32_e32 v26, v22, v25
	v_and_b32_e32 v10, 0xffff0000, v100
	s_waitcnt vmcnt(1)
	v_lshlrev_b32_e32 v25, 16, v104
	v_fmac_f32_e32 v26, v5, v25
	s_waitcnt vmcnt(0)
; __device__ __forceinline__ unsigned cvt_pk_bf16(float lo, float hi) { unsigned r; asm("v_cvt_pk_bf16_f32 %0, %1, %2" : "=v"(r) : "v"(lo), "v"(hi)); return r; }
; __device__ __forceinline__ float bf_lo(unsigned u) { return __uint_as_float(u << 16); }
; __device__ __forceinline__ float bf_hi(unsigned u) { return __uint_as_float(u & 0xffff0000u); }
; __device__ __forceinline__ float sigmoidf_(float x) { return 1.f / (1.f + __expf(-x)); }
; __device__ __forceinline__ void phase_attn_combine(const bf16_t* __restrict__ qh, const bf16_t* __restrict__ gate, const float* __restrict__ lse, bf16_t* __restrict__ y, const int S) {
;     ...
;     const unsigned au[4] = {a.x, a.y, a.z, a.w}, bu[4] = {b.x, b.y, b.z, b.w}, cu[4] = {c.x, c.y, c.z, c.w}, gu[4] = {gt.x, gt.y, gt.z, gt.w};
;     unsigned ou[4];
; #pragma unroll
;     for (int k = 0; k < 4; ++k) {
;       const float g0 = bf_lo(gu[k]), g1 = bf_hi(gu[k]);
;       const float y0 = (w0 * bf_lo(au[k]) + w1 * bf_lo(bu[k]) + w2 * bf_lo(cu[k])) * g0 * sigmoidf_(g0);
;       const float y1 = (w0 * bf_hi(au[k]) + w1 * bf_hi(bu[k]) + w2 * bf_hi(cu[k])) * g1 * sigmoidf_(g1);
;       ou[k] = cvt_pk_bf16(y0, y1);
;     }
;     uint4 o; o.x = ou[0]; o.y = ou[1]; o.z = ou[2]; o.w = ou[3];
;     *(uint4*)(y + t * 2048 + col) = o;
	v_lshlrev_b32_e32 v24, 16, v108
	v_mul_f32_e32 v25, v26, v24
	v_mul_f32_e32 v24, 0xbfb8aa3b, v24
	v_exp_f32_e32 v24, v24
	v_mul_f32_e32 v10, v23, v10
	v_fmac_f32_e32 v10, v22, v6
	v_and_b32_e32 v6, 0xffff0000, v104
	v_add_f32_e32 v24, 1.0, v24
	v_div_scale_f32 v26, s[18:19], v24, v24, 1.0
	v_and_b32_e32 v18, 0xffff0000, v108
	v_rcp_f32_e32 v27, v26
	v_fmac_f32_e32 v10, v5, v6
	v_mul_f32_e32 v6, v10, v18
	v_mul_f32_e32 v10, 0xbfb8aa3b, v18
	v_exp_f32_e32 v10, v10
	v_fma_f32 v28, -v26, v27, 1.0
	v_fmac_f32_e32 v27, v28, v27
	v_div_scale_f32 v28, vcc, 1.0, v24, 1.0
	v_mul_f32_e32 v29, v28, v27
	v_add_f32_e32 v10, 1.0, v10
	v_fma_f32 v30, -v26, v29, v28
	v_div_scale_f32 v14, s[18:19], v10, v10, 1.0
	v_fmac_f32_e32 v29, v30, v27
	v_rcp_f32_e32 v18, v14
	v_fma_f32 v26, -v26, v29, v28
	v_div_fmas_f32 v26, v26, v27, v29
	v_div_fixup_f32 v24, v26, v24, 1.0
	v_mul_f32_e32 v24, v25, v24
	v_fma_f32 v25, -v14, v18, 1.0
	v_fmac_f32_e32 v18, v25, v18
	v_div_scale_f32 v25, vcc, 1.0, v10, 1.0
	v_mul_f32_e32 v26, v25, v18
	v_fma_f32 v27, -v14, v26, v25
	v_fmac_f32_e32 v26, v27, v18
	v_fma_f32 v14, -v14, v26, v25
	v_div_fmas_f32 v14, v14, v18, v26
	v_div_fixup_f32 v10, v14, v10, 1.0
	v_mul_f32_e32 v6, v6, v10
	v_lshlrev_b32_e32 v10, 16, v109
	v_and_b32_e32 v14, 0xffff0000, v109
	v_lshlrev_b32_e32 v19, 16, v101
	v_lshlrev_b32_e32 v18, 16, v97
	v_mul_f32_e32 v19, v23, v19
	v_fmac_f32_e32 v19, v22, v18
	v_lshlrev_b32_e32 v18, 16, v105
	v_fmac_f32_e32 v19, v5, v18
	v_mul_f32_e32 v18, v19, v10
	v_mul_f32_e32 v10, 0xbfb8aa3b, v10
	v_exp_f32_e32 v10, v10
	v_and_b32_e32 v11, 0xffff0000, v101
	v_and_b32_e32 v7, 0xffff0000, v97
	v_mul_f32_e32 v11, v23, v11
	v_add_f32_e32 v10, 1.0, v10
	v_div_scale_f32 v19, s[18:19], v10, v10, 1.0
	v_fmac_f32_e32 v11, v22, v7
	v_and_b32_e32 v7, 0xffff0000, v105
	v_cvt_pk_bf16_f32 v6, v24, v6
	v_rcp_f32_e32 v24, v19
	v_fmac_f32_e32 v11, v5, v7
	v_mul_f32_e32 v7, v11, v14
	v_mul_f32_e32 v11, 0xbfb8aa3b, v14
	v_exp_f32_e32 v11, v11
	v_fma_f32 v25, -v19, v24, 1.0
	v_fmac_f32_e32 v24, v25, v24
	v_div_scale_f32 v25, vcc, 1.0, v10, 1.0
	v_mul_f32_e32 v26, v25, v24
	v_add_f32_e32 v11, 1.0, v11
	v_fma_f32 v27, -v19, v26, v25
	v_div_scale_f32 v14, s[18:19], v11, v11, 1.0
	v_fmac_f32_e32 v26, v27, v24
	v_rcp_f32_e32 v15, v14
	v_fma_f32 v19, -v19, v26, v25
	v_div_fmas_f32 v19, v19, v24, v26
	v_div_fixup_f32 v10, v19, v10, 1.0
	v_mul_f32_e32 v10, v18, v10
	v_fma_f32 v18, -v14, v15, 1.0
	v_fmac_f32_e32 v15, v18, v15
	v_div_scale_f32 v18, vcc, 1.0, v11, 1.0
	v_mul_f32_e32 v19, v18, v15
	v_fma_f32 v24, -v14, v19, v18
	v_fmac_f32_e32 v19, v24, v15
	v_fma_f32 v14, -v14, v19, v18
	v_div_fmas_f32 v14, v14, v15, v19
	v_lshlrev_b32_e32 v15, 16, v102
	v_div_fixup_f32 v11, v14, v11, 1.0
	v_lshlrev_b32_e32 v14, 16, v98
	v_mul_f32_e32 v15, v23, v15
	v_mul_f32_e32 v7, v7, v11
	v_fmac_f32_e32 v15, v22, v14
	v_lshlrev_b32_e32 v14, 16, v106
	v_cvt_pk_bf16_f32 v7, v10, v7
	v_lshlrev_b32_e32 v10, 16, v110
	v_fmac_f32_e32 v15, v5, v14
	v_mul_f32_e32 v14, v15, v10
	v_mul_f32_e32 v10, 0xbfb8aa3b, v10
	v_exp_f32_e32 v10, v10
	v_and_b32_e32 v12, 0xffff0000, v102
	v_and_b32_e32 v8, 0xffff0000, v98
	v_mul_f32_e32 v12, v23, v12
	v_add_f32_e32 v10, 1.0, v10
	v_div_scale_f32 v15, s[18:19], v10, v10, 1.0
	v_rcp_f32_e32 v18, v15
	v_fmac_f32_e32 v12, v22, v8
	v_and_b32_e32 v8, 0xffff0000, v106
	v_and_b32_e32 v11, 0xffff0000, v110
	v_fma_f32 v19, -v15, v18, 1.0
	v_fmac_f32_e32 v12, v5, v8
	v_fmac_f32_e32 v18, v19, v18
	v_div_scale_f32 v19, vcc, 1.0, v10, 1.0
	v_mul_f32_e32 v8, v12, v11
	v_mul_f32_e32 v11, 0xbfb8aa3b, v11
	v_mul_f32_e32 v20, v19, v18
	v_exp_f32_e32 v11, v11
	v_fma_f32 v24, -v15, v20, v19
	v_fmac_f32_e32 v20, v24, v18
	v_fma_f32 v15, -v15, v20, v19
	v_div_fmas_f32 v15, v15, v18, v20
	v_add_f32_e32 v11, 1.0, v11
	v_div_fixup_f32 v10, v15, v10, 1.0
	v_div_scale_f32 v12, s[18:19], v11, v11, 1.0
	v_mul_f32_e32 v10, v14, v10
	v_rcp_f32_e32 v14, v12
	s_nop 0
	v_fma_f32 v15, -v12, v14, 1.0
	v_fmac_f32_e32 v14, v15, v14
	v_div_scale_f32 v15, vcc, 1.0, v11, 1.0
	v_mul_f32_e32 v16, v15, v14
	v_fma_f32 v18, -v12, v16, v15
	v_fmac_f32_e32 v16, v18, v14
	v_fma_f32 v12, -v12, v16, v15
	v_div_fmas_f32 v12, v12, v14, v16
	v_lshlrev_b32_e32 v14, 16, v103
	v_div_fixup_f32 v11, v12, v11, 1.0
	v_lshlrev_b32_e32 v12, 16, v99
	v_mul_f32_e32 v14, v23, v14
	v_mul_f32_e32 v8, v8, v11
	v_fmac_f32_e32 v14, v22, v12
	v_lshlrev_b32_e32 v12, 16, v107
	v_cvt_pk_bf16_f32 v8, v10, v8
	v_lshlrev_b32_e32 v10, 16, v111
	v_fmac_f32_e32 v14, v5, v12
	v_mul_f32_e32 v12, v14, v10
	v_mul_f32_e32 v10, 0xbfb8aa3b, v10
	v_exp_f32_e32 v10, v10
	v_and_b32_e32 v9, 0xffff0000, v99
	v_and_b32_e32 v11, 0xffff0000, v111
	v_add_f32_e32 v10, 1.0, v10
	v_div_scale_f32 v14, s[18:19], v10, v10, 1.0
	v_rcp_f32_e32 v15, v14
	s_nop 0
	v_fma_f32 v16, -v14, v15, 1.0
	v_fmac_f32_e32 v15, v16, v15
	v_div_scale_f32 v16, vcc, 1.0, v10, 1.0
	v_mul_f32_e32 v18, v16, v15
	v_fma_f32 v19, -v14, v18, v16
	v_fmac_f32_e32 v18, v19, v15
	v_fma_f32 v14, -v14, v18, v16
	v_div_fmas_f32 v14, v14, v15, v18
	v_div_fixup_f32 v10, v14, v10, 1.0
	v_mul_f32_e32 v10, v12, v10
	v_and_b32_e32 v12, 0xffff0000, v103
	v_mul_f32_e32 v12, v23, v12
	v_fmac_f32_e32 v12, v22, v9
	v_and_b32_e32 v9, 0xffff0000, v107
	v_fmac_f32_e32 v12, v5, v9
	v_mul_f32_e32 v9, 0xbfb8aa3b, v11
	v_exp_f32_e32 v9, v9
	v_mul_f32_e32 v5, v12, v11
	v_add_f32_e32 v9, 1.0, v9
	v_div_scale_f32 v11, s[18:19], v9, v9, 1.0
	v_rcp_f32_e32 v12, v11
	s_mov_b64 s[18:19], 0x3fffff
	v_fma_f32 v13, -v11, v12, 1.0
	v_fmac_f32_e32 v12, v13, v12
	v_div_scale_f32 v13, vcc, 1.0, v9, 1.0
	v_mul_f32_e32 v14, v13, v12
	v_fma_f32 v15, -v11, v14, v13
	v_fmac_f32_e32 v14, v15, v12
	v_fma_f32 v11, -v11, v14, v13
	v_div_fmas_f32 v11, v11, v12, v14
	v_cmp_lt_u64_e32 vcc, s[18:19], v[0:1]
	v_div_fixup_f32 v9, v11, v9, 1.0
	s_or_b64 s[92:93], vcc, s[92:93]
	v_mul_f32_e32 v5, v5, v9
	v_cvt_pk_bf16_f32 v9, v10, v5
	global_store_dwordx4 v[2:3], v[6:9], off
	s_andn2_b64 exec, exec, s[92:93]
	s_cbranch_execnz .LBB0_775
